# v23 + attention O stores widened: v_permlane32_swap pairs -> global_store_dwordx4 (diff 16->8, MoBA 8->4 stores per lane)
# speedup vs baseline: 1.0063x; 1.0000x over previous
; __device__ __forceinline__ void diff_unit(int b, int hd, int qb, const bf16_t* Q, const bf16_t* K, const bf16_t* VT, bf16_t* O, const float* biasd, float lam, const float* subg, ALAS unsigned char* lds) {
;     ...
;     if (map == 1) {
; #pragma unroll
;         for (int d = 0; d < 4; ++d)
; #pragma unroll
;             for (int r = 0; r < 16; ++r) X[((w4 * 4 + d) * 16 + r) * 64 + lane] = o[d][r] * inv;
;     }
;     __syncthreads();
;     if (map == 0) {
;         float sq = 0.f;
; #pragma unroll
;         for (int d = 0; d < 4; ++d)
; #pragma unroll
;             for (int r = 0; r < 16; ++r) { const float a = o[d][r] * inv - lam * X[((w4 * 4 + d) * 16 + r) * 64 + lane]; o[d][r] = a; sq += a * a; }
.LBB0_514:
	s_cmpk_gt_u32 s7, 0xff
	s_waitcnt lgkmcnt(0)
	s_barrier
	s_cbranch_scc1 .LBB0_494
	s_lshl_b32 s4, s7, 8
	v_lshl_add_u32 v68, v64, 2, 0
	s_and_b32 s7, s4, 0xc000
	v_add_u32_e32 v69, s7, v68
	ds_read2st64_b32 v[108:109], v69 offset1:1
	ds_read2st64_b32 v[106:107], v69 offset0:2 offset1:3
	s_waitcnt vmcnt(2)
	ds_read2st64_b32 v[122:123], v69 offset0:4 offset1:5
	ds_read2st64_b32 v[114:115], v69 offset0:6 offset1:7
	s_waitcnt vmcnt(0)
	ds_read2st64_b32 v[124:125], v69 offset0:8 offset1:9
	ds_read2st64_b32 v[156:157], v69 offset0:10 offset1:11
	ds_read2st64_b32 v[138:139], v69 offset0:12 offset1:13
	ds_read2st64_b32 v[142:143], v69 offset0:14 offset1:15
	ds_read2st64_b32 v[126:127], v69 offset0:16 offset1:17
	ds_read2st64_b32 v[140:141], v69 offset0:18 offset1:19
	ds_read2st64_b32 v[118:119], v69 offset0:20 offset1:21
	ds_read2st64_b32 v[136:137], v69 offset0:22 offset1:23
	ds_read2st64_b32 v[110:111], v69 offset0:24 offset1:25
	ds_read2st64_b32 v[120:121], v69 offset0:26 offset1:27
	ds_read2st64_b32 v[100:101], v69 offset0:28 offset1:29
	ds_read2st64_b32 v[112:113], v69 offset0:30 offset1:31
	ds_read2st64_b32 v[96:97], v69 offset0:32 offset1:33
	ds_read2st64_b32 v[104:105], v69 offset0:34 offset1:35
	ds_read2st64_b32 v[92:93], v69 offset0:36 offset1:37
	ds_read2st64_b32 v[98:99], v69 offset0:38 offset1:39
	ds_read2st64_b32 v[88:89], v69 offset0:40 offset1:41
	ds_read2st64_b32 v[94:95], v69 offset0:42 offset1:43
	ds_read2st64_b32 v[86:87], v69 offset0:44 offset1:45
	ds_read2st64_b32 v[90:91], v69 offset0:46 offset1:47
	ds_read2st64_b32 v[82:83], v69 offset0:48 offset1:49
	ds_read2st64_b32 v[84:85], v69 offset0:50 offset1:51
	ds_read2st64_b32 v[76:77], v69 offset0:52 offset1:53
	ds_read2st64_b32 v[80:81], v69 offset0:54 offset1:55
	ds_read2st64_b32 v[74:75], v69 offset0:56 offset1:57
	ds_read2st64_b32 v[64:65], v69 offset0:58 offset1:59
	s_waitcnt lgkmcnt(14)
	v_pk_mul_f32 v[106:107], v[128:129], v[106:107]
	s_or_b32 s4, s4, 0x3f00
	v_pk_fma_f32 v[106:107], v[50:51], v[70:71], v[106:107] op_sel_hi:[1,0,1] neg_lo:[0,0,1] neg_hi:[0,0,1]
	v_pk_mul_f32 v[50:51], v[128:129], v[108:109]
	s_waitcnt lgkmcnt(0)
	v_pk_mul_f32 v[64:65], v[128:129], v[64:65]
	v_pk_fma_f32 v[116:117], v[48:49], v[70:71], v[50:51] op_sel_hi:[1,0,1] neg_lo:[0,0,1] neg_hi:[0,0,1]
	v_pk_mul_f32 v[48:49], v[128:129], v[114:115]
	v_pk_fma_f32 v[64:65], v[10:11], v[70:71], v[64:65] op_sel_hi:[1,0,1] neg_lo:[0,0,1] neg_hi:[0,0,1]
	v_pk_fma_f32 v[114:115], v[54:55], v[70:71], v[48:49] op_sel_hi:[1,0,1] neg_lo:[0,0,1] neg_hi:[0,0,1]
	v_pk_mul_f32 v[48:49], v[128:129], v[122:123]
	ds_read2st64_b32 v[10:11], v69 offset0:60 offset1:61
	v_pk_fma_f32 v[122:123], v[52:53], v[70:71], v[48:49] op_sel_hi:[1,0,1] neg_lo:[0,0,1] neg_hi:[0,0,1]
	v_pk_mul_f32 v[48:49], v[128:129], v[156:157]
	v_mov_b32_e32 v135, v145
	v_pk_fma_f32 v[108:109], v[58:59], v[70:71], v[48:49] op_sel_hi:[1,0,1] neg_lo:[0,0,1] neg_hi:[0,0,1]
	v_pk_mul_f32 v[48:49], v[128:129], v[124:125]
	s_waitcnt lgkmcnt(0)
	v_pk_mul_f32 v[10:11], v[128:129], v[10:11]
	v_pk_fma_f32 v[124:125], v[56:57], v[70:71], v[48:49] op_sel_hi:[1,0,1] neg_lo:[0,0,1] neg_hi:[0,0,1]
	v_pk_mul_f32 v[48:49], v[128:129], v[142:143]
	v_pk_fma_f32 v[66:67], v[12:13], v[70:71], v[10:11] op_sel_hi:[1,0,1] neg_lo:[0,0,1] neg_hi:[0,0,1]
	v_pk_fma_f32 v[56:57], v[62:63], v[70:71], v[48:49] op_sel_hi:[1,0,1] neg_lo:[0,0,1] neg_hi:[0,0,1]
	v_pk_mul_f32 v[48:49], v[128:129], v[138:139]
	v_add_u32_e32 v11, s4, v68
	v_pk_fma_f32 v[60:61], v[60:61], v[70:71], v[48:49] op_sel_hi:[1,0,1] neg_lo:[0,0,1] neg_hi:[0,0,1]
	v_pk_mul_f32 v[48:49], v[128:129], v[140:141]
	ds_read_b32 v10, v69 offset:15872
	ds_read_b32 v11, v11
	v_pk_fma_f32 v[52:53], v[34:35], v[70:71], v[48:49] op_sel_hi:[1,0,1] neg_lo:[0,0,1] neg_hi:[0,0,1]
	v_pk_mul_f32 v[34:35], v[128:129], v[126:127]
	s_lshl_b32 s4, s6, 1
	v_pk_fma_f32 v[58:59], v[32:33], v[70:71], v[34:35] op_sel_hi:[1,0,1] neg_lo:[0,0,1] neg_hi:[0,0,1]
	v_pk_mul_f32 v[32:33], v[128:129], v[136:137]
	s_waitcnt lgkmcnt(0)
	v_pk_mul_f32 v[10:11], v[128:129], v[10:11]
	v_pk_fma_f32 v[48:49], v[38:39], v[70:71], v[32:33] op_sel_hi:[1,0,1] neg_lo:[0,0,1] neg_hi:[0,0,1]
	v_pk_mul_f32 v[32:33], v[128:129], v[118:119]
	v_pk_fma_f32 v[68:69], v[14:15], v[70:71], v[10:11] op_sel_hi:[1,0,1] neg_lo:[0,0,1] neg_hi:[0,0,1]
	v_pk_fma_f32 v[54:55], v[36:37], v[70:71], v[32:33] op_sel_hi:[1,0,1] neg_lo:[0,0,1] neg_hi:[0,0,1]
	v_pk_mul_f32 v[32:33], v[128:129], v[120:121]
	v_lshl_add_u64 v[10:11], v[132:133], 1, s[92:93]
	v_pk_fma_f32 v[42:43], v[42:43], v[70:71], v[32:33] op_sel_hi:[1,0,1] neg_lo:[0,0,1] neg_hi:[0,0,1]
	v_pk_mul_f32 v[32:33], v[128:129], v[110:111]
	v_lshl_add_u64 v[10:11], v[10:11], 0, s[4:5]
	v_pk_fma_f32 v[50:51], v[40:41], v[70:71], v[32:33] op_sel_hi:[1,0,1] neg_lo:[0,0,1] neg_hi:[0,0,1]
	v_pk_mul_f32 v[32:33], v[128:129], v[112:113]
	v_lshl_add_u64 v[14:15], v[10:11], 0, v[134:135]
	v_pk_fma_f32 v[38:39], v[46:47], v[70:71], v[32:33] op_sel_hi:[1,0,1] neg_lo:[0,0,1] neg_hi:[0,0,1]
	v_pk_mul_f32 v[32:33], v[128:129], v[100:101]
	global_load_dwordx4 v[10:13], v130, s[76:77]
	global_load_dwordx4 v[172:175], v130, s[76:77] offset:32
	global_load_dwordx4 v[176:179], v130, s[76:77] offset:64
	global_load_dwordx4 v[180:183], v130, s[76:77] offset:96
	global_load_dwordx4 v[184:187], v130, s[76:77] offset:128
	global_load_dwordx4 v[188:191], v130, s[76:77] offset:160
	global_load_dwordx4 v[192:195], v130, s[76:77] offset:192
	global_load_dwordx4 v[196:199], v130, s[76:77] offset:224
	global_load_dwordx4 v[216:219], v130, s[76:77] offset:256
	global_load_dwordx4 v[220:223], v130, s[76:77] offset:288
; __device__ __forceinline__ void diff_unit(int b, int hd, int qb, const bf16_t* Q, const bf16_t* K, const bf16_t* VT, bf16_t* O, const float* biasd, float lam, const float* subg, ALAS unsigned char* lds) {
;     ...
;         for (int d = 0; d < 4; ++d)
; #pragma unroll
;             for (int r = 0; r < 16; ++r) { const float a = o[d][r] * inv - lam * X[((w4 * 4 + d) * 16 + r) * 64 + lane]; o[d][r] = a; sq += a * a; }
;         sq += __shfl_xor(sq, 32);
;         const float rn = __builtin_amdgcn_rsqf(sq * (1.0f / 128.0f) + SUBLN_EPS) * 0.8f;
	global_load_dwordx4 v[224:227], v130, s[76:77] offset:320
	global_load_dwordx4 v[228:231], v130, s[76:77] offset:352
	global_load_dwordx4 v[232:235], v130, s[76:77] offset:384
	global_load_dwordx4 v[236:239], v130, s[76:77] offset:416
	global_load_dwordx4 v[240:243], v130, s[76:77] offset:448
	global_load_dwordx4 v[244:247], v130, s[76:77] offset:480
	v_pk_fma_f32 v[44:45], v[44:45], v[70:71], v[32:33] op_sel_hi:[1,0,1] neg_lo:[0,0,1] neg_hi:[0,0,1]
	v_pk_mul_f32 v[32:33], v[128:129], v[104:105]
	v_pk_mul_f32 v[134:135], v[116:117], v[116:117]
	v_pk_fma_f32 v[34:35], v[18:19], v[70:71], v[32:33] op_sel_hi:[1,0,1] neg_lo:[0,0,1] neg_hi:[0,0,1]
	v_pk_mul_f32 v[18:19], v[128:129], v[96:97]
	v_pk_mul_f32 v[132:133], v[106:107], v[106:107]
	v_pk_fma_f32 v[40:41], v[16:17], v[70:71], v[18:19] op_sel_hi:[1,0,1] neg_lo:[0,0,1] neg_hi:[0,0,1]
	v_pk_mul_f32 v[16:17], v[128:129], v[98:99]
	v_pk_mul_f32 v[160:161], v[122:123], v[122:123]
	v_pk_fma_f32 v[32:33], v[22:23], v[70:71], v[16:17] op_sel_hi:[1,0,1] neg_lo:[0,0,1] neg_hi:[0,0,1]
	v_pk_mul_f32 v[16:17], v[128:129], v[92:93]
	v_pk_mul_f32 v[158:159], v[114:115], v[114:115]
	v_pk_fma_f32 v[36:37], v[20:21], v[70:71], v[16:17] op_sel_hi:[1,0,1] neg_lo:[0,0,1] neg_hi:[0,0,1]
	v_pk_mul_f32 v[16:17], v[128:129], v[94:95]
	v_pk_mul_f32 v[162:163], v[124:125], v[124:125]
	v_pk_fma_f32 v[22:23], v[26:27], v[70:71], v[16:17] op_sel_hi:[1,0,1] neg_lo:[0,0,1] neg_hi:[0,0,1]
	v_pk_mul_f32 v[16:17], v[128:129], v[88:89]
	v_pk_mul_f32 v[156:157], v[108:109], v[108:109]
	v_pk_fma_f32 v[26:27], v[24:25], v[70:71], v[16:17] op_sel_hi:[1,0,1] neg_lo:[0,0,1] neg_hi:[0,0,1]
	v_pk_mul_f32 v[16:17], v[128:129], v[90:91]
	v_pk_mul_f32 v[138:139], v[60:61], v[60:61]
	v_pk_fma_f32 v[18:19], v[30:31], v[70:71], v[16:17] op_sel_hi:[1,0,1] neg_lo:[0,0,1] neg_hi:[0,0,1]
	v_pk_mul_f32 v[16:17], v[128:129], v[86:87]
	v_pk_mul_f32 v[62:63], v[56:57], v[56:57]
	v_pk_fma_f32 v[24:25], v[28:29], v[70:71], v[16:17] op_sel_hi:[1,0,1] neg_lo:[0,0,1] neg_hi:[0,0,1]
	v_pk_mul_f32 v[16:17], v[128:129], v[84:85]
	v_pk_mul_f32 v[126:127], v[58:59], v[58:59]
	v_pk_fma_f32 v[16:17], v[2:3], v[70:71], v[16:17] op_sel_hi:[1,0,1] neg_lo:[0,0,1] neg_hi:[0,0,1]
	v_pk_mul_f32 v[2:3], v[128:129], v[82:83]
	v_pk_mul_f32 v[140:141], v[52:53], v[52:53]
	v_pk_fma_f32 v[20:21], v[0:1], v[70:71], v[2:3] op_sel_hi:[1,0,1] neg_lo:[0,0,1] neg_hi:[0,0,1]
	v_pk_mul_f32 v[0:1], v[128:129], v[80:81]
	v_pk_mul_f32 v[118:119], v[54:55], v[54:55]
	v_pk_fma_f32 v[2:3], v[6:7], v[70:71], v[0:1] op_sel_hi:[1,0,1] neg_lo:[0,0,1] neg_hi:[0,0,1]
	v_pk_mul_f32 v[0:1], v[128:129], v[76:77]
	v_pk_mul_f32 v[136:137], v[48:49], v[48:49]
	v_pk_fma_f32 v[4:5], v[4:5], v[70:71], v[0:1] op_sel_hi:[1,0,1] neg_lo:[0,0,1] neg_hi:[0,0,1]
	v_pk_mul_f32 v[0:1], v[128:129], v[74:75]
	v_pk_mul_f32 v[110:111], v[50:51], v[50:51]
	v_pk_fma_f32 v[0:1], v[8:9], v[70:71], v[0:1] op_sel_hi:[1,0,1] neg_lo:[0,0,1] neg_hi:[0,0,1]
	v_add_f32_e32 v70, v134, v135
	v_add_f32_e32 v70, v70, v132
	v_add_f32_e32 v70, v70, v133
	v_add_f32_e32 v70, v70, v160
	v_add_f32_e32 v70, v70, v161
	v_add_f32_e32 v70, v70, v158
	v_add_f32_e32 v70, v70, v159
	v_add_f32_e32 v70, v70, v162
	v_add_f32_e32 v70, v70, v163
	v_add_f32_e32 v70, v70, v156
	v_add_f32_e32 v70, v70, v157
	v_add_f32_e32 v70, v70, v138
	v_add_f32_e32 v70, v70, v139
	v_add_f32_e32 v62, v70, v62
	v_add_f32_e32 v62, v62, v63
	v_add_f32_e32 v62, v62, v126
	v_add_f32_e32 v62, v62, v127
	v_add_f32_e32 v62, v62, v140
	v_add_f32_e32 v62, v62, v141
	v_add_f32_e32 v62, v62, v118
	v_add_f32_e32 v62, v62, v119
	v_add_f32_e32 v62, v62, v136
	v_add_f32_e32 v62, v62, v137
	v_add_f32_e32 v62, v62, v110
	v_pk_mul_f32 v[120:121], v[42:43], v[42:43]
	v_add_f32_e32 v62, v62, v111
	v_add_f32_e32 v62, v62, v120
	v_pk_mul_f32 v[100:101], v[44:45], v[44:45]
	v_add_f32_e32 v62, v62, v121
	v_add_f32_e32 v62, v62, v100
	v_pk_mul_f32 v[46:47], v[38:39], v[38:39]
	v_add_f32_e32 v62, v62, v101
	v_add_f32_e32 v46, v62, v46
	v_pk_mul_f32 v[96:97], v[40:41], v[40:41]
	v_add_f32_e32 v46, v46, v47
	v_add_f32_e32 v46, v46, v96
	v_pk_mul_f32 v[104:105], v[34:35], v[34:35]
	v_add_f32_e32 v46, v46, v97
	v_add_f32_e32 v46, v46, v104
	v_pk_mul_f32 v[92:93], v[36:37], v[36:37]
	v_add_f32_e32 v46, v46, v105
	v_add_f32_e32 v46, v46, v92
	v_pk_mul_f32 v[98:99], v[32:33], v[32:33]
	v_add_f32_e32 v46, v46, v93
	v_add_f32_e32 v46, v46, v98
	v_pk_mul_f32 v[88:89], v[26:27], v[26:27]
	v_add_f32_e32 v46, v46, v99
	v_add_f32_e32 v46, v46, v88
	v_pk_mul_f32 v[94:95], v[22:23], v[22:23]
	v_add_f32_e32 v46, v46, v89
	v_add_f32_e32 v46, v46, v94
	v_pk_mul_f32 v[28:29], v[24:25], v[24:25]
	v_add_f32_e32 v46, v46, v95
	v_add_f32_e32 v28, v46, v28
	v_pk_mul_f32 v[30:31], v[18:19], v[18:19]
	v_add_f32_e32 v28, v28, v29
	v_add_f32_e32 v28, v28, v30
	v_pk_mul_f32 v[82:83], v[20:21], v[20:21]
	v_add_f32_e32 v28, v28, v31
	v_add_f32_e32 v28, v28, v82
	v_pk_mul_f32 v[84:85], v[16:17], v[16:17]
	v_add_f32_e32 v28, v28, v83
	v_add_f32_e32 v28, v28, v84
	v_pk_mul_f32 v[76:77], v[4:5], v[4:5]
	v_add_f32_e32 v28, v28, v85
	v_add_f32_e32 v28, v28, v76
	v_pk_mul_f32 v[6:7], v[2:3], v[2:3]
	v_add_f32_e32 v28, v28, v77
	v_add_f32_e32 v6, v28, v6
	v_pk_mul_f32 v[8:9], v[0:1], v[0:1]
	v_add_f32_e32 v6, v6, v7
	v_add_f32_e32 v6, v6, v8
	v_pk_mul_f32 v[72:73], v[64:65], v[64:65]
	v_add_f32_e32 v6, v6, v9
	v_add_f32_e32 v6, v6, v72
	v_pk_mul_f32 v[78:79], v[66:67], v[66:67]
	v_add_f32_e32 v6, v6, v73
	v_add_f32_e32 v6, v6, v78
	v_pk_mul_f32 v[102:103], v[68:69], v[68:69]
	v_add_f32_e32 v6, v6, v79
	v_add_f32_e32 v6, v6, v102
	v_add_f32_e32 v6, v6, v103
	ds_bpermute_b32 v7, v170, v6
	s_waitcnt lgkmcnt(0)
; __device__ __forceinline__ unsigned cvtpk(float lo, float hi) { return pg8::cvt_pk_bf16(lo, hi); }
; __device__ __forceinline__ void diff_unit(int b, int hd, int qb, const bf16_t* Q, const bf16_t* K, const bf16_t* VT, bf16_t* O, const float* biasd, float lam, const float* subg, ALAS unsigned char* lds) {
;     ...
;         sq += __shfl_xor(sq, 32);
;         const float rn = __builtin_amdgcn_rsqf(sq * (1.0f / 128.0f) + SUBLN_EPS) * 0.8f;
;         bf16_t* op = O + (tok0 + qpos) * 1024 + hd * 128 + 4 * hi;
; #pragma unroll
;         for (int d = 0; d < 4; ++d)
; #pragma unroll
;             for (int a4 = 0; a4 < 4; ++a4) { const int c0 = d * 32 + 8 * a4; const pg8::f32x4 g4 = *(const pg8::f32x4*)(subg + c0 + 4 * hi); u32x2 w;
;                 w.x = cvtpk(o[d][4 * a4 + 0] * rn * g4[0], o[d][4 * a4 + 1] * rn * g4[1]); w.y = cvtpk(o[d][4 * a4 + 2] * rn * g4[2], o[d][4 * a4 + 3] * rn * g4[3]);
;                 *(u32x2*)(op + c0) = w; }
	v_add_f32_e32 v6, v6, v7
	v_mov_b32_e32 v7, 0x3727c5ac
	v_fmamk_f32 v6, v6, 0x3c000000, v7
	v_rsq_f32_e32 v6, v6
	s_nop 0
	v_mul_f32_e32 v6, 0x3f4ccccd, v6
	v_pk_mul_f32 v[8:9], v[116:117], v[6:7] op_sel_hi:[1,0]
	v_pk_mul_f32 v[4:5], v[4:5], v[6:7] op_sel_hi:[1,0]
	s_waitcnt vmcnt(15)
	v_pk_mul_f32 v[8:9], v[10:11], v[8:9]
	v_pk_mul_f32 v[10:11], v[106:107], v[6:7] op_sel_hi:[1,0]
	v_and_b32_e32 v252, 32, v203
	v_lshrrev_b32_e32 v252, 2, v252
	v_add_co_u32_e32 v252, vcc, v14, v252
	s_nop 1
	v_addc_co_u32_e32 v253, vcc, 0, v15, vcc
	v_cvt_pk_bf16_f32 v248, v8, v9
	v_pk_mul_f32 v[10:11], v[12:13], v[10:11]
	v_pk_mul_f32 v[12:13], v[122:123], v[6:7] op_sel_hi:[1,0]
	v_cvt_pk_bf16_f32 v249, v10, v11
	v_pk_mul_f32 v[2:3], v[2:3], v[6:7] op_sel_hi:[1,0]
	v_pk_mul_f32 v[0:1], v[0:1], v[6:7] op_sel_hi:[1,0]
	s_waitcnt vmcnt(14)
	v_pk_mul_f32 v[8:9], v[172:173], v[12:13]
	v_pk_mul_f32 v[12:13], v[114:115], v[6:7] op_sel_hi:[1,0]
	v_cvt_pk_bf16_f32 v250, v8, v9
	v_pk_mul_f32 v[10:11], v[174:175], v[12:13]
	v_pk_mul_f32 v[12:13], v[124:125], v[6:7] op_sel_hi:[1,0]
	v_cvt_pk_bf16_f32 v251, v10, v11
	s_nop 1
	v_permlane32_swap_b32 v248, v250
	v_permlane32_swap_b32 v249, v251
	global_store_dwordx4 v[252:253], v[248:251], off
	s_nop 1
	s_waitcnt vmcnt(14)
	v_pk_mul_f32 v[8:9], v[176:177], v[12:13]
	v_pk_mul_f32 v[12:13], v[108:109], v[6:7] op_sel_hi:[1,0]
	v_cvt_pk_bf16_f32 v248, v8, v9
	v_pk_mul_f32 v[10:11], v[178:179], v[12:13]
	v_pk_mul_f32 v[12:13], v[60:61], v[6:7] op_sel_hi:[1,0]
	v_cvt_pk_bf16_f32 v249, v10, v11
	s_waitcnt vmcnt(13)
	v_pk_mul_f32 v[8:9], v[180:181], v[12:13]
	v_pk_mul_f32 v[12:13], v[56:57], v[6:7] op_sel_hi:[1,0]
	v_cvt_pk_bf16_f32 v250, v8, v9
	v_pk_mul_f32 v[10:11], v[182:183], v[12:13]
	v_pk_mul_f32 v[12:13], v[58:59], v[6:7] op_sel_hi:[1,0]
	v_cvt_pk_bf16_f32 v251, v10, v11
	s_nop 1
	v_permlane32_swap_b32 v248, v250
	v_permlane32_swap_b32 v249, v251
	global_store_dwordx4 v[252:253], v[248:251], off offset:32
	s_nop 1
	s_waitcnt vmcnt(13)
	v_pk_mul_f32 v[8:9], v[184:185], v[12:13]
	v_pk_mul_f32 v[12:13], v[52:53], v[6:7] op_sel_hi:[1,0]
	v_cvt_pk_bf16_f32 v248, v8, v9
	v_pk_mul_f32 v[10:11], v[186:187], v[12:13]
	v_pk_mul_f32 v[12:13], v[54:55], v[6:7] op_sel_hi:[1,0]
	v_cvt_pk_bf16_f32 v249, v10, v11
	s_waitcnt vmcnt(12)
	v_pk_mul_f32 v[8:9], v[12:13], v[188:189]
	v_pk_mul_f32 v[12:13], v[48:49], v[6:7] op_sel_hi:[1,0]
	v_cvt_pk_bf16_f32 v250, v8, v9
	v_pk_mul_f32 v[10:11], v[12:13], v[190:191]
	v_pk_mul_f32 v[12:13], v[50:51], v[6:7] op_sel_hi:[1,0]
	v_cvt_pk_bf16_f32 v251, v10, v11
	s_nop 1
	v_permlane32_swap_b32 v248, v250
	v_permlane32_swap_b32 v249, v251
	global_store_dwordx4 v[252:253], v[248:251], off offset:64
	s_nop 1
	s_waitcnt vmcnt(12)
	v_pk_mul_f32 v[8:9], v[12:13], v[192:193]
	v_pk_mul_f32 v[12:13], v[42:43], v[6:7] op_sel_hi:[1,0]
	v_cvt_pk_bf16_f32 v248, v8, v9
	v_pk_mul_f32 v[10:11], v[12:13], v[194:195]
	v_pk_mul_f32 v[12:13], v[44:45], v[6:7] op_sel_hi:[1,0]
	v_cvt_pk_bf16_f32 v249, v10, v11
	s_waitcnt vmcnt(11)
	v_pk_mul_f32 v[8:9], v[12:13], v[196:197]
	v_pk_mul_f32 v[12:13], v[38:39], v[6:7] op_sel_hi:[1,0]
	v_cvt_pk_bf16_f32 v250, v8, v9
	v_pk_mul_f32 v[10:11], v[12:13], v[198:199]
	v_pk_mul_f32 v[12:13], v[40:41], v[6:7] op_sel_hi:[1,0]
	v_cvt_pk_bf16_f32 v251, v10, v11
	s_nop 1
	v_permlane32_swap_b32 v248, v250
	v_permlane32_swap_b32 v249, v251
	global_store_dwordx4 v[252:253], v[248:251], off offset:96
	s_nop 1
	s_waitcnt vmcnt(11)
	v_pk_mul_f32 v[8:9], v[12:13], v[216:217]
	v_pk_mul_f32 v[12:13], v[34:35], v[6:7] op_sel_hi:[1,0]
	v_cvt_pk_bf16_f32 v248, v8, v9
	v_pk_mul_f32 v[10:11], v[12:13], v[218:219]
	v_pk_mul_f32 v[12:13], v[36:37], v[6:7] op_sel_hi:[1,0]
	v_cvt_pk_bf16_f32 v249, v10, v11
	s_waitcnt vmcnt(10)
	v_pk_mul_f32 v[8:9], v[12:13], v[220:221]
	v_pk_mul_f32 v[12:13], v[32:33], v[6:7] op_sel_hi:[1,0]
	v_cvt_pk_bf16_f32 v250, v8, v9
	v_pk_mul_f32 v[10:11], v[12:13], v[222:223]
	v_pk_mul_f32 v[12:13], v[26:27], v[6:7] op_sel_hi:[1,0]
	v_cvt_pk_bf16_f32 v251, v10, v11
	s_nop 1
	v_permlane32_swap_b32 v248, v250
	v_permlane32_swap_b32 v249, v251
	global_store_dwordx4 v[252:253], v[248:251], off offset:128
	s_nop 1
	s_waitcnt vmcnt(10)
	v_pk_mul_f32 v[8:9], v[12:13], v[224:225]
	v_pk_mul_f32 v[12:13], v[22:23], v[6:7] op_sel_hi:[1,0]
	v_cvt_pk_bf16_f32 v248, v8, v9
	v_pk_mul_f32 v[10:11], v[12:13], v[226:227]
	v_pk_mul_f32 v[12:13], v[24:25], v[6:7] op_sel_hi:[1,0]
	v_cvt_pk_bf16_f32 v249, v10, v11
	s_waitcnt vmcnt(9)
	v_pk_mul_f32 v[8:9], v[12:13], v[228:229]
	v_pk_mul_f32 v[12:13], v[18:19], v[6:7] op_sel_hi:[1,0]
	v_cvt_pk_bf16_f32 v250, v8, v9
	v_pk_mul_f32 v[10:11], v[12:13], v[230:231]
	v_pk_mul_f32 v[12:13], v[20:21], v[6:7] op_sel_hi:[1,0]
	v_cvt_pk_bf16_f32 v251, v10, v11
	s_nop 1
	v_permlane32_swap_b32 v248, v250
	v_permlane32_swap_b32 v249, v251
	global_store_dwordx4 v[252:253], v[248:251], off offset:160
	s_nop 1
	s_waitcnt vmcnt(9)
	v_pk_mul_f32 v[8:9], v[12:13], v[232:233]
	v_pk_mul_f32 v[12:13], v[16:17], v[6:7] op_sel_hi:[1,0]
	v_cvt_pk_bf16_f32 v248, v8, v9
	v_pk_mul_f32 v[10:11], v[12:13], v[234:235]
	s_nop 0
	v_cvt_pk_bf16_f32 v249, v10, v11
	s_waitcnt vmcnt(8)
	v_pk_mul_f32 v[4:5], v[4:5], v[236:237]
	v_pk_mul_f32 v[2:3], v[2:3], v[238:239]
	v_cvt_pk_bf16_f32 v250, v4, v5
	v_cvt_pk_bf16_f32 v251, v2, v3
	s_nop 1
	v_permlane32_swap_b32 v248, v250
	v_permlane32_swap_b32 v249, v251
	global_store_dwordx4 v[252:253], v[248:251], off offset:192
	s_nop 1
	s_waitcnt vmcnt(8)
	v_pk_mul_f32 v[0:1], v[0:1], v[240:241]
	v_pk_mul_f32 v[2:3], v[64:65], v[6:7] op_sel_hi:[1,0]
	v_cvt_pk_bf16_f32 v248, v0, v1
	v_pk_mul_f32 v[2:3], v[2:3], v[242:243]
	v_pk_mul_f32 v[4:5], v[66:67], v[6:7] op_sel_hi:[1,0]
	v_cvt_pk_bf16_f32 v249, v2, v3
	s_waitcnt vmcnt(7)
	v_pk_mul_f32 v[0:1], v[4:5], v[244:245]
	v_pk_mul_f32 v[4:5], v[68:69], v[6:7] op_sel_hi:[1,0]
	v_cvt_pk_bf16_f32 v250, v0, v1
	v_pk_mul_f32 v[2:3], v[4:5], v[246:247]
	s_nop 0
	v_cvt_pk_bf16_f32 v251, v2, v3
	s_nop 1
	v_permlane32_swap_b32 v248, v250
	v_permlane32_swap_b32 v249, v251
	global_store_dwordx4 v[252:253], v[248:251], off offset:224
	s_nop 1
	s_branch .LBB0_494

; __device__ __forceinline__ unsigned cvtpk(float lo, float hi) { return pg8::cvt_pk_bf16(lo, hi); }
; __device__ __forceinline__ void moba_unit(int b, int h, int j, const bf16_t* Q, const bf16_t* K, const bf16_t* VT, bf16_t* O, const float* biasd, const float* kmean, ALAS unsigned char* lds) {
;     ...
;     lsum += __shfl_xor(lsum, 32);
;     const float inv = 1.0f / lsum;
;     bf16_t* op = O + (tok0 + qpos) * 1024 + h * 64 + 4 * hi;
; #pragma unroll
;     for (int d = 0; d < 2; ++d)
; #pragma unroll
;         for (int a4 = 0; a4 < 4; ++a4) { u32x2 w; w.x = cvtpk(o[d][4 * a4 + 0] * inv, o[d][4 * a4 + 1] * inv); w.y = cvtpk(o[d][4 * a4 + 2] * inv, o[d][4 * a4 + 3] * inv);
;             *(u32x2*)(op + d * 32 + 8 * a4) = w; }
.LBB0_517:
	ds_bpermute_b32 v34, v93, v100
	v_lshlrev_b64 v[32:33], 10, v[88:89]
	v_lshl_add_u64 v[32:33], v[32:33], 1, s[92:93]
	s_lshl_b32 s4, s58, 1
	v_lshl_add_u64 v[32:33], v[32:33], 0, s[4:5]
	s_waitcnt lgkmcnt(0)
	v_add_f32_e32 v34, v100, v34
	v_div_scale_f32 v35, s[0:1], v34, v34, 1.0
	v_rcp_f32_e32 v36, v35
	v_div_scale_f32 v37, vcc, 1.0, v34, 1.0
	v_mov_b32_e32 v99, v145
	v_fma_f32 v38, -v35, v36, 1.0
	v_fmac_f32_e32 v36, v38, v36
	v_mul_f32_e32 v38, v37, v36
	v_fma_f32 v39, -v35, v38, v37
	v_fmac_f32_e32 v38, v39, v36
	v_fma_f32 v35, -v35, v38, v37
	v_div_fmas_f32 v35, v35, v36, v38
	v_div_fixup_f32 v34, v35, v34, 1.0
	v_lshl_add_u64 v[32:33], v[32:33], 0, v[98:99]
	v_and_b32_e32 v35, 32, v203
	v_lshrrev_b32_e32 v35, 2, v35
	v_add_co_u32_e32 v32, vcc, v32, v35
	s_nop 1
	v_addc_co_u32_e32 v33, vcc, 0, v33, vcc
	s_mov_b64 s[96:97], s[74:75]
	v_pk_mul_f32 v[16:17], v[16:17], v[34:35] op_sel_hi:[1,0]
	v_pk_mul_f32 v[18:19], v[18:19], v[34:35] op_sel_hi:[1,0]
	v_pk_mul_f32 v[20:21], v[20:21], v[34:35] op_sel_hi:[1,0]
	v_pk_mul_f32 v[22:23], v[22:23], v[34:35] op_sel_hi:[1,0]
	v_cvt_pk_bf16_f32 v36, v16, v17
	v_cvt_pk_bf16_f32 v37, v18, v19
	v_cvt_pk_bf16_f32 v38, v20, v21
	v_cvt_pk_bf16_f32 v39, v22, v23
	s_nop 1
	v_permlane32_swap_b32 v36, v38
	v_permlane32_swap_b32 v37, v39
	global_store_dwordx4 v[32:33], v[36:39], off
	v_pk_mul_f32 v[24:25], v[24:25], v[34:35] op_sel_hi:[1,0]
	v_pk_mul_f32 v[26:27], v[26:27], v[34:35] op_sel_hi:[1,0]
	v_pk_mul_f32 v[28:29], v[28:29], v[34:35] op_sel_hi:[1,0]
	v_pk_mul_f32 v[30:31], v[30:31], v[34:35] op_sel_hi:[1,0]
	v_cvt_pk_bf16_f32 v36, v24, v25
	v_cvt_pk_bf16_f32 v37, v26, v27
	v_cvt_pk_bf16_f32 v38, v28, v29
	v_cvt_pk_bf16_f32 v39, v30, v31
	s_nop 1
	v_permlane32_swap_b32 v36, v38
	v_permlane32_swap_b32 v37, v39
	global_store_dwordx4 v[32:33], v[36:39], off offset:32
	v_pk_mul_f32 v[0:1], v[0:1], v[34:35] op_sel_hi:[1,0]
	v_pk_mul_f32 v[2:3], v[2:3], v[34:35] op_sel_hi:[1,0]
	v_pk_mul_f32 v[4:5], v[4:5], v[34:35] op_sel_hi:[1,0]
	v_pk_mul_f32 v[6:7], v[6:7], v[34:35] op_sel_hi:[1,0]
	v_cvt_pk_bf16_f32 v36, v0, v1
	v_cvt_pk_bf16_f32 v37, v2, v3
	v_cvt_pk_bf16_f32 v38, v4, v5
	v_cvt_pk_bf16_f32 v39, v6, v7
	s_nop 1
	v_permlane32_swap_b32 v36, v38
	v_permlane32_swap_b32 v37, v39
	global_store_dwordx4 v[32:33], v[36:39], off offset:64
	v_pk_mul_f32 v[8:9], v[8:9], v[34:35] op_sel_hi:[1,0]
	v_pk_mul_f32 v[10:11], v[10:11], v[34:35] op_sel_hi:[1,0]
	v_pk_mul_f32 v[12:13], v[12:13], v[34:35] op_sel_hi:[1,0]
	v_pk_mul_f32 v[14:15], v[14:15], v[34:35] op_sel_hi:[1,0]
	v_cvt_pk_bf16_f32 v36, v8, v9
	v_cvt_pk_bf16_f32 v37, v10, v11
	v_cvt_pk_bf16_f32 v38, v12, v13
	v_cvt_pk_bf16_f32 v39, v14, v15
	s_nop 1
	v_permlane32_swap_b32 v36, v38
	v_permlane32_swap_b32 v37, v39
	global_store_dwordx4 v[32:33], v[36:39], off offset:96
	s_setprio 0
	v_readlane_b32 s0, v254, 1
	s_add_i32 s36, s36, s0
	s_cmpk_lt_i32 s36, 0x800
	s_barrier
	v_readlane_b32 s1, v254, 2
	s_cbranch_scc0 .LBB0_490
